# plus phase A of layers 1..3 on all workgroups
# speedup vs baseline: 1.0038x; 1.0038x over previous
;     __device__ __forceinline__ const float* in(int i) const { return (const float*)(const __attribute__((address_space(1))) float*)get(i); }
;     __device__ __forceinline__ unsigned char* ws() const { return (unsigned char*)(__attribute__((address_space(1))) unsigned char*)get(35); }
; #define RUN(REPS, GSEL, ...) _Pragma("unroll 1") for (int rep_ = 0; rep_ < (REPS); ++rep_) { { const int Gsel = (GSEL); if (bid0 < Gsel) { __VA_ARGS__ } } GRID_BAR(); }
; __device__ __forceinline__ void rs2_rows(const PA& a, int gtid, int nthr, int nrows, size_t rs_off = WS_RS2) {
;     const f32x4* ps = (const f32x4*)(a.ws() + WS_PS); float* rs = (float*)(a.ws() + rs_off);
;     for (int r = gtid; r < nrows; r += nthr) { float s = 0.f;
; #pragma unroll
;         for (int j = 0; j < 8; ++j) { const f32x4 p = ps[(size_t)r * 8 + j]; s += (p.x + p.y) + (p.z + p.w); }
;         rs[r] = 1.f / sqrtf(s * (1.f / D) + EPS); }
; __global__ void __launch_bounds__(512, 2) mega_fwd(Args args) {
;     ...
;         RUN(1, (l == 0 ? Ggemm : Gthin),
;             if (l == 0) {
;             { PH_BEGIN for (int u = bid; u < 32; u += G) s5_tables_unit(a, l, u, ldsL, tid); }
;             { PH_BEGIN norm_rows(a, l, 1, gw, NGW, lane, NTOK); neutral_norm1(a, bid * 512 + tid, G * 512); } }
;             else {
;             { PH_BEGIN rs2_rows(a, bid * 512 + tid, G * 512, NLAT, WS_RS1); norm_ctx_rows(a, l, gw, NGW, lane); }
;             { PH_BEGIN shw_rows(a, l, 0, WSP(const bf16, WS_WIN), INC, WSP(float, WS_SHWIN), nullptr, ldsL, tid, gw, NGW); }
;             { PH_BEGIN shw_rows(a, l, 0, WSP(const bf16, WS_WG), DFF, WSP(float, WS_SHWG), a.in(I_BGATE) + (size_t)l * 4 * D, ldsL, tid, gw, NGW); } } )
.LBB0_163:
	s_cmp_lg_u32 s96, 0
	s_cselect_b64 s[0:1], -1, 0
	v_writelane_b32 v254, s0, 34
	s_cmp_eq_u32 s96, 0
	s_mov_b32 s22, s87
	v_writelane_b32 v254, s1, 35
	s_mul_i32 s0, s96, 0x3c000
	s_lshl_b32 s4, s96, 11
	v_writelane_b32 v254, s0, 36
	s_mov_b32 s5, s59
	v_writelane_b32 v254, s4, 37
	s_cmp_ge_i32 s81, s22
	s_nop 0
	v_writelane_b32 v254, s5, 38
	s_cbranch_scc1 .LBB0_269
	v_readlane_b32 s4, v254, 34
	v_readlane_b32 s5, v254, 35
	s_mov_b64 s[0:1], -1
	s_and_b64 vcc, exec, s[4:5]
	s_cbranch_vccz .LBB0_202
	s_mov_b32 s15, s81
	s_mov_b32 s14, s22
	s_mov_b32 s0, s93
	v_mbcnt_lo_u32_b32 v0, -1, 0
	v_mbcnt_hi_u32_b32 v0, -1, v0
	s_nop 0
	v_lshl_or_b32 v6, s0, 6, v0
	v_mov_b32 v0, 0
	s_nop 0
	v_add_u32_e32 v0, s79, v0
	ds_read_b32 v1, v0 offset:280
	ds_read_b32 v0, v0 offset:284
	s_waitcnt lgkmcnt(1)
	v_mov_b32 v1, 0
	s_waitcnt lgkmcnt(0)
	v_lshl_add_u32 v0, s15, 9, v6
	v_add_u32_e32 v1, s79, v1
	ds_read_b32 v2, v1 offset:280
	ds_read_b32 v1, v1 offset:284
	v_readfirstlane_b32 s16, v6
	v_cmp_gt_i32_e32 vcc, s80, v0
	s_waitcnt lgkmcnt(1)
	v_readfirstlane_b32 s0, v2
	s_waitcnt lgkmcnt(0)
	v_readfirstlane_b32 s1, v1
	v_mov_b32 v1, 0
	s_nop 0
	v_add_u32_e32 v1, s79, v1
	ds_read_b32 v2, v1 offset:280
	ds_read_b32 v1, v1 offset:284
	s_waitcnt lgkmcnt(1)
	v_readfirstlane_b32 s7, v2
	s_waitcnt lgkmcnt(0)
	v_readfirstlane_b32 s8, v1
	s_and_saveexec_b64 s[4:5], vcc
	s_cbranch_execz .LBB0_168
	v_ashrrev_i32_e32 v1, 31, v0
	s_lshl_b32 s6, s14, 9
	v_mov_b32_e32 v2, s7
	v_mov_b32_e32 v3, s8
	v_lshlrev_b64 v[4:5], 7, v[0:1]
	v_lshl_add_u64 v[2:3], v[0:1], 2, v[2:3]
	s_mov_b64 s[8:9], 0x56600000
	s_ashr_i32 s7, s6, 31
	v_lshl_add_u64 v[4:5], s[0:1], 0, v[4:5]
	s_mov_b64 s[0:1], 0x55c00070
	v_lshl_add_u64 v[2:3], v[2:3], 0, s[8:9]
	s_lshl_b64 s[8:9], s[6:7], 2
	v_lshl_add_u64 v[4:5], v[4:5], 0, s[0:1]
	s_lshl_b64 s[10:11], s[6:7], 7
	s_mov_b64 s[12:13], 0
